# attention staging loads use scalar tile base + constant per-lane offset (no per-tile 64-bit address VALU), diff+GQA loops, on top of v36
# speedup vs baseline: 1.0064x; 1.0064x over previous
; #define LAS __attribute__((address_space(3)))
; template <int KIND> ...
;     ...
;         { const bf16_t* qp = qkv + (size_t)(qrow0 + qoff + l32) * N + hq * 64 + 8 * hi;
; #pragma unroll
;           for (int t = 0; t < 4; ++t) qf[t] = *(const bf16x8*)(qp + 16 * t); }
;         if (KIND == 0 && !isctx) { LAS float* bt = (LAS float*)(lds + OFF_BIAS); for (int i = tid; i < 465; i += NTHREADS) bt[i] = rpb[h * 465 + i] * LOG2E; }
;         u32x4 kreg[NK], vreg[NVC];
;         const int krow_l = tid >> 3, kpart = tid & 7;
;     ...
;         float m_ref = 0.f; int first = 1;
;         f32x16 o[NDT], lacc, mneg;
; #pragma unroll
;         for (int dt = 0; dt < NDT; ++dt)
; #pragma unroll
;             for (int j = 0; j < 16; ++j) o[dt][j] = 0.f;
; #pragma unroll
;         for (int j = 0; j < 16; ++j) { lacc[j] = 0.f; mneg[j] = 0.f; }
;         const bf16x8 ones = {(short)0x3F80, (short)0x3F80, (short)0x3F80, (short)0x3F80, (short)0x3F80, (short)0x3F80, (short)0x3F80, (short)0x3F80};
;         ATT_LOAD(0); ATT_STORE(0); __syncthreads();
;         const int koff = kidx * KT + l32 * KSTR + 16 * hi;
;         const int voff = OFF_V + (4 * hi + ((lane & 15) >> 2)) * VSTR + (16 * ((lane >> 4) & 1) + 4 * (lane & 3)) * 2;
;         const int wb = 4 * hi - cs;
;         const int boff0 = OFF_BIAS + 4 * (cs - qc + 15 + wb);
.LBB0_97:
	s_and_b64 s[2:3], s[6:7], exec
	s_movk_i32 s2, 0x880
	s_cselect_b32 s2, s2, 0x800
	s_cmp_ge_i32 s74, s2
	s_cbranch_scc1 .LBB0_171
	v_ashrrev_i32_e32 v3, 31, v198
	v_lshrrev_b32_e32 v3, 29, v3
	v_add_u32_e32 v3, v198, v3
	s_waitcnt vmcnt(0)
	v_ashrrev_i32_e32 v151, 3, v198
	v_and_b32_e32 v2, 7, v196
	v_ashrrev_i32_e32 v152, 3, v3
	v_and_b32_e32 v3, -8, v3
	v_sub_u32_e32 v3, v198, v3
	v_mul_lo_u32 v4, v151, s90
	v_lshlrev_b32_e32 v192, 4, v2
	s_movk_i32 s4, 0xc0
	v_ashrrev_i32_e32 v1, 5, v196
	v_lshlrev_b32_e32 v0, 3, v2
	v_lshlrev_b32_e32 v138, 3, v3
	v_add3_u32 v153, 0, v4, v192
	v_mul_lo_u32 v2, v152, s4
	v_lshlrev_b32_e32 v3, 4, v3
	v_bfe_u32 v4, v196, 2, 2
	v_lshlrev_b32_e32 v136, 3, v1
	v_add3_u32 v154, 0, v2, v3
	v_lshlrev_b32_e32 v3, 4, v1
	v_lshl_or_b32 v1, v1, 2, v4
	v_and_b32_e32 v4, 16, v196
	v_lshlrev_b32_e32 v5, 2, v196
	v_and_or_b32 v4, v5, 12, v4
	v_and_b32_e32 v150, 31, v196
	v_mul_lo_u32 v1, v1, s4
	v_lshlrev_b32_e32 v4, 1, v4
	v_cmp_lt_i32_e32 vcc, v223, v217
	v_ashrrev_i32_e32 v139, 31, v138
	v_mul_u32_u24_e32 v2, 0x90, v150
	v_add3_u32 v156, 0, v1, v4
	s_mul_i32 s4, s38, 0x1200
	v_cndmask_b32_e32 v1, v216, v223, vcc
	s_lshl_b32 s3, s38, 5
	v_ashrrev_i32_e32 v137, 31, v136
	v_add3_u32 v155, 0, v2, v3
	v_lshl_add_u64 v[140:141], s[58:59], 0, v[192:193]
	v_lshl_add_u64 v[142:143], v[138:139], 1, s[58:59]
	s_add_i32 s14, s4, 0
	v_lshlrev_b32_e32 v157, 2, v1
	v_add_u32_e32 v158, 0x80, v152
	v_add_u32_e32 v159, 0x80, v151
	v_lshlrev_b32_e32 v144, 1, v0
	v_mul_u32_u24_e32 v184, 0xc00, v151
	v_and_b32_e32 v185, 7, v196
	v_lshl_add_u32 v184, v185, 4, v184
	s_mov_b32 s15, s74
	s_branch .LBB0_100

; #define LAS __attribute__((address_space(3)))
; template <int KIND> ...
;     ...
;         { const bf16_t* qp = qkv + (size_t)(qrow0 + qoff + l32) * N + hq * 64 + 8 * hi;
; #pragma unroll
;           for (int t = 0; t < 4; ++t) qf[t] = *(const bf16x8*)(qp + 16 * t); }
;         if (KIND == 0 && !isctx) { LAS float* bt = (LAS float*)(lds + OFF_BIAS); for (int i = tid; i < 465; i += NTHREADS) bt[i] = rpb[h * 465 + i] * LOG2E; }
;         u32x4 kreg[NK], vreg[NVC];
;         const int krow_l = tid >> 3, kpart = tid & 7;
;     ...
;         float m_ref = 0.f; int first = 1;
;         f32x16 o[NDT], lacc, mneg;
; #pragma unroll
;         for (int dt = 0; dt < NDT; ++dt)
; #pragma unroll
;             for (int j = 0; j < 16; ++j) o[dt][j] = 0.f;
; #pragma unroll
;         for (int j = 0; j < 16; ++j) { lacc[j] = 0.f; mneg[j] = 0.f; }
;         const bf16x8 ones = {(short)0x3F80, (short)0x3F80, (short)0x3F80, (short)0x3F80, (short)0x3F80, (short)0x3F80, (short)0x3F80, (short)0x3F80};
;         ATT_LOAD(0); ATT_STORE(0); __syncthreads();
;     ...
;                 for (int t4 = 0; t4 < 4; ++t4) { kf[2 * t4] = *(const LAS bf16x8*)(lds + buf * KBUF + koff + 32 * t4); kf[2 * t4 + 1] = *(const LAS bf16x8*)(lds + buf * KBUF + koff + 32 * KSTR + 32 * t4); }
;                 __builtin_amdgcn_sched_barrier(0);
;                 f32x16 s0, s1;
; #pragma unroll
;                 for (int t4 = 0; t4 < 4; ++t4) {
;                     s0 = __builtin_amdgcn_mfma_f32_32x32x16_bf16(kf[2 * t4], qf[t4], t4 == 0 ? mneg : s0, 0, 0, 0);
;                     s1 = __builtin_amdgcn_mfma_f32_32x32x16_bf16(kf[2 * t4 + 1], qf[t4], t4 == 0 ? mneg : s1, 0, 0, 0);
;                 }
;                 float ab0[16], ab1[16];
;                 const bool na_lat = (KIND == 0) && (t < n1);
;                 if (na_lat) {
;                     const int bo = boff0 + (kr_lo + t - qr + 7) * 124;
; #pragma unroll
;                     for (int j = 0; j < 16; ++j) {
;                         const int C0 = 8 * (j >> 2) + (j & 3), C1 = 32 + C0;
;                         const float b0 = *(const LAS float*)(lds + bo + 4 * C0), b1 = *(const LAS float*)(lds + bo + 4 * C1);
;                         ab0[j] = ((unsigned)(wb + C0) < 16u) ? b0 : -1e30f;
;                         ab1[j] = ((unsigned)(wb + C1) < 16u) ? b1 : -1e30f;
;                     }
; #pragma unroll
.LBB0_108:
	s_add_i32 s16, s19, 0x8000
	s_add_i32 s4, s20, s3
	s_lshl_b32 s12, s17, 6
	s_lshl_b32 s96, s17, 7
	v_add_u32_e32 v2, s4, v150
	v_mov_b64_e32 v[0:1], s[58:59]
	s_and_b64 s[20:21], s[10:11], exec
	v_mad_i64_i32 v[2:3], s[20:21], v2, s23, v[0:1]
	s_cselect_b32 s22, s13, s16
	v_lshl_add_u64 v[8:9], v[2:3], 0, s[96:97]
	v_add_u32_e32 v2, s22, v151
	s_lshl_b32 s17, s17, 5
	v_add_u32_e32 v4, s22, v152
	v_mad_i64_i32 v[2:3], s[20:21], v2, s23, v[0:1]
	s_and_b32 s96, s17, 0xffffff80
	v_mad_i64_i32 v[0:1], s[20:21], v4, s23, v[0:1]
	v_lshl_add_u64 v[2:3], v[2:3], 0, s[96:97]
	v_mov_b32_e32 v145, v193
	v_lshl_add_u64 v[0:1], v[0:1], 0, s[96:97]
	v_lshl_add_u64 v[2:3], v[2:3], 0, v[144:145]
	v_lshl_add_u64 v[4:5], v[138:139], 1, v[0:1]
	global_load_dwordx4 v[0:3], v[2:3], off offset:2048
	s_or_b32 s17, s13, 64
	global_load_dwordx4 v[4:7], v[4:5], off offset:2560
	s_add_i32 s19, s19, 0x8040
	s_and_b64 s[10:11], s[10:11], exec
	v_lshl_add_u64 v[8:9], v[136:137], 1, v[8:9]
	s_cselect_b32 s10, s17, s19
	v_lshl_add_u64 v[148:149], v[140:141], 0, s[96:97]
	v_lshl_add_u64 v[146:147], v[142:143], 0, s[96:97]
	s_add_u32 s36, s58, s96
	s_addc_u32 s37, s59, 0
	s_add_u32 s36, s36, 0x800
	s_addc_u32 s37, s37, 0
	global_load_dwordx4 v[116:119], v[8:9], off
	global_load_dwordx4 v[112:115], v[8:9], off offset:32
	global_load_dwordx4 v[108:111], v[8:9], off offset:64
	global_load_dwordx4 v[104:107], v[8:9], off offset:96
	v_add_u32_e32 v8, s10, v151
	v_add_u32_e32 v10, s10, v152
	v_mad_i64_i32 v[8:9], s[10:11], v8, s23, v[148:149]
	v_mad_i64_i32 v[10:11], s[10:11], v10, s23, v[146:147]
	s_waitcnt vmcnt(5)
	ds_write_b128 v153, v[0:3]
	s_waitcnt vmcnt(4)
	ds_write_b128 v154, v[4:7] offset:18432
	s_waitcnt lgkmcnt(0)
	s_barrier
	global_load_dwordx4 v[64:67], v[8:9], off offset:2048
	global_load_dwordx4 v[68:71], v[10:11], off offset:2560
	ds_read_b128 v[0:3], v155
	ds_read_b128 v[32:35], v155 offset:32
	ds_read_b128 v[16:19], v155 offset:4608
	ds_read_b128 v[36:39], v155 offset:4640
	ds_read_b128 v[40:43], v155 offset:64
	ds_read_b128 v[44:47], v155 offset:96
	ds_read_b128 v[48:51], v155 offset:4672
	ds_read_b128 v[52:55], v155 offset:4704
	s_waitcnt vmcnt(5) lgkmcnt(7)
	v_mfma_f32_32x32x16_bf16 v[0:15], v[0:3], v[116:119], 0
	ds_read_b64_tr_b16 v[72:73], v156 offset:18432
	ds_read_b64_tr_b16 v[74:75], v156 offset:19968
	ds_read_b64_tr_b16 v[78:79], v156 offset:20032
	ds_read_b64_tr_b16 v[76:77], v156 offset:18496
	ds_read_b64_tr_b16 v[80:81], v156 offset:21504
	ds_read_b64_tr_b16 v[82:83], v156 offset:23040
	ds_read_b64_tr_b16 v[86:87], v156 offset:23104
	s_waitcnt lgkmcnt(12)
	v_mfma_f32_32x32x16_bf16 v[16:31], v[16:19], v[116:119], 0
	ds_read_b64_tr_b16 v[84:85], v156 offset:21568
	s_waitcnt vmcnt(4)
	v_mfma_f32_32x32x16_bf16 v[0:15], v[32:35], v[112:115], v[0:15]
	s_waitcnt lgkmcnt(12)
	v_mfma_f32_32x32x16_bf16 v[16:31], v[36:39], v[112:115], v[16:31]
	s_waitcnt vmcnt(3) lgkmcnt(11)
	v_mfma_f32_32x32x16_bf16 v[0:15], v[40:43], v[108:111], v[0:15]
	s_waitcnt lgkmcnt(9)
	v_mfma_f32_32x32x16_bf16 v[16:31], v[48:51], v[108:111], v[16:31]
	s_waitcnt vmcnt(2)
	v_mfma_f32_32x32x16_bf16 v[0:15], v[44:47], v[104:107], v[0:15]
	s_waitcnt lgkmcnt(8)
	v_mfma_f32_32x32x16_bf16 v[16:31], v[52:55], v[104:107], v[16:31]
	s_nop 9
	v_max_f32_e32 v32, v15, v15
	s_nop 0
	v_max_f32_e32 v33, v31, v31
	v_max_f32_e32 v32, v33, v32
	v_max3_f32 v33, v32, v0, v16
	v_max3_f32 v32, v32, v1, v17
	s_nop 0
	v_max3_f32 v33, v33, v2, v18
	v_max3_f32 v32, v32, v3, v19
	s_nop 0
	v_max3_f32 v33, v33, v4, v20
	v_max3_f32 v32, v32, v5, v21
	s_nop 0
	v_max3_f32 v33, v33, v6, v22
	v_max3_f32 v32, v32, v7, v23
	s_nop 0
	v_max3_f32 v33, v33, v8, v24
	v_max3_f32 v32, v32, v9, v25
	s_nop 0
	v_max3_f32 v33, v33, v10, v26
	v_max3_f32 v32, v32, v11, v27
	s_nop 0
	v_max3_f32 v33, v33, v12, v28
	v_max3_f32 v32, v32, v13, v29
	s_nop 0
	v_max3_f32 v33, v33, v14, v30
	v_max3_f32 v32, v32, v15, v31
	s_nop 0
	v_max_f32_e32 v32, v32, v32
	v_max_f32_e32 v33, v33, v33
	v_max_f32_e32 v32, v33, v32
	ds_bpermute_b32 v33, v157, v32
	s_waitcnt lgkmcnt(0)
	v_max_f32_e32 v33, v33, v33
	v_max_f32_e32 v48, v32, v33
	v_sub_f32_e32 v0, v0, v48
	v_sub_f32_e32 v1, v1, v48
	v_sub_f32_e32 v2, v2, v48
	v_sub_f32_e32 v3, v3, v48
	v_sub_f32_e32 v4, v4, v48
	v_sub_f32_e32 v5, v5, v48
	v_sub_f32_e32 v6, v6, v48
	v_sub_f32_e32 v7, v7, v48
	v_sub_f32_e32 v8, v8, v48
	v_sub_f32_e32 v9, v9, v48
	v_sub_f32_e32 v10, v10, v48
	v_sub_f32_e32 v11, v11, v48
	v_sub_f32_e32 v12, v12, v48
	v_sub_f32_e32 v13, v13, v48
	v_sub_f32_e32 v14, v14, v48
	v_sub_f32_e32 v15, v15, v48
	v_exp_f32_e32 v0, v0
	v_exp_f32_e32 v1, v1
	v_exp_f32_e32 v2, v2
	v_exp_f32_e32 v3, v3
	v_exp_f32_e32 v4, v4
	v_exp_f32_e32 v5, v5
	v_exp_f32_e32 v6, v6
	v_exp_f32_e32 v7, v7
	v_exp_f32_e32 v8, v8
	v_exp_f32_e32 v9, v9
	v_exp_f32_e32 v10, v10
	v_exp_f32_e32 v11, v11
	v_exp_f32_e32 v12, v12
	v_exp_f32_e32 v13, v13
	v_exp_f32_e32 v14, v14
	v_exp_f32_e32 v15, v15
	v_sub_f32_e32 v32, 0, v48
	v_sub_f32_e32 v16, v16, v48
	v_sub_f32_e32 v17, v17, v48
	v_sub_f32_e32 v18, v18, v48
	v_sub_f32_e32 v19, v19, v48
	v_mov_b32_e32 v33, v32
	v_mov_b32_e32 v34, v32
	v_mov_b32_e32 v35, v32
	v_mov_b32_e32 v36, v32
	v_mov_b32_e32 v37, v32
	v_mov_b32_e32 v38, v32
	v_mov_b32_e32 v39, v32
	v_mov_b32_e32 v40, v32
	v_mov_b32_e32 v41, v32
	v_mov_b32_e32 v42, v32
	v_mov_b32_e32 v43, v32
	v_mov_b32_e32 v44, v32
	v_mov_b32_e32 v45, v32
	v_mov_b32_e32 v46, v32
	v_mov_b32_e32 v47, v32
	v_cvt_pk_bf16_f32 v0, v0, v1
	v_cvt_pk_bf16_f32 v1, v2, v3
	v_cvt_pk_bf16_f32 v2, v4, v5
	v_cvt_pk_bf16_f32 v3, v6, v7
	v_sub_f32_e32 v96, v20, v48
	v_sub_f32_e32 v97, v21, v48
	v_sub_f32_e32 v98, v22, v48
; template <int KIND> ...
;     ...
; #pragma unroll
;                 for (int j = 0; j < 16; ++j) s0[j] = __builtin_amdgcn_exp2f(s0[j]);
;                 bf16x8 pf[4];
; #pragma unroll
;                 for (int s = 0; s < 2; ++s) { u32x4 w; w.x = pk2n(s0[8 * s + 0], s0[8 * s + 1]); w.y = pk2n(s0[8 * s + 2], s0[8 * s + 3]); w.z = pk2n(s0[8 * s + 4], s0[8 * s + 5]); w.w = pk2n(s0[8 * s + 6], s0[8 * s + 7]);
;                     pf[s] = __builtin_bit_cast(bf16x8, w); }
;                 __builtin_amdgcn_sched_barrier(0);
; #pragma unroll
;                 for (int s = 0; s < 2; ++s)
; #pragma unroll
;                     for (int dt = 0; dt < NDT; ++dt) {
;                         vfb[s][dt][0] = __builtin_amdgcn_ds_read_tr16_b64_v4i16((LAS s16x4*)(lds + buf * VBUF + voff + (16 * (s + 2)) * VSTR + 64 * dt));
;                         vfb[s][dt][1] = __builtin_amdgcn_ds_read_tr16_b64_v4i16((LAS s16x4*)(lds + buf * VBUF + voff + (16 * (s + 2) + 8) * VSTR + 64 * dt)); }
;                 {
;                     constexpr int NM = 2 * (1 + NDT);
;                     int mi = 0;
; #pragma unroll
;                     for (int s = 0; s < 2; ++s) {
;                         lacc = __builtin_amdgcn_mfma_f32_32x32x16_bf16(ones, pf[s], lacc, 0, 0, 0);
; #pragma unroll
;                         for (int j = (mi * 16) / NM; j < ((mi + 1) * 16) / NM; ++j) s1[j] = __builtin_amdgcn_exp2f(s1[j]);
;                         ++mi;
; #pragma unroll
;                         for (int dt = 0; dt < NDT; ++dt) {
;                             const s16x4 va = vfa[s][dt][0], vb = vfa[s][dt][1];
;                             const bf16x8 vf = {va[0], va[1], va[2], va[3], vb[0], vb[1], vb[2], vb[3]};
;                             o[dt] = __builtin_amdgcn_mfma_f32_32x32x16_bf16(vf, pf[s], o[dt], 0, 0, 0);
; #pragma unroll
;                             for (int j = (mi * 16) / NM; j < ((mi + 1) * 16) / NM; ++j) s1[j] = __builtin_amdgcn_exp2f(s1[j]);
;                             ++mi;
;                         }
;                     }
; #pragma unroll
;                     for (int q = 0; q < 2; ++q) { u32x4 w; w.x = pk2n(s1[8 * q + 0], s1[8 * q + 1]); w.y = pk2n(s1[8 * q + 2], s1[8 * q + 3]); w.z = pk2n(s1[8 * q + 4], s1[8 * q + 5]); w.w = pk2n(s1[8 * q + 6], s1[8 * q + 7]);
;                         pf[q + 2] = __builtin_bit_cast(bf16x8, w); }
; #pragma unroll
	v_sub_f32_e32 v99, v23, v48
	v_sub_f32_e32 v100, v24, v48
	v_sub_f32_e32 v101, v25, v48
	v_sub_f32_e32 v102, v26, v48
	v_sub_f32_e32 v103, v27, v48
	v_sub_f32_e32 v120, v28, v48
	v_sub_f32_e32 v121, v29, v48
	v_sub_f32_e32 v122, v30, v48
	v_sub_f32_e32 v123, v31, v48
	v_cvt_pk_bf16_f32 v88, v8, v9
	v_cvt_pk_bf16_f32 v89, v10, v11
	v_cvt_pk_bf16_f32 v90, v12, v13
	v_cvt_pk_bf16_f32 v91, v14, v15
	v_mov_b64_e32 v[94:95], s[86:87]
	v_mov_b64_e32 v[92:93], s[84:85]
	v_exp_f32_e32 v124, v16
	v_exp_f32_e32 v125, v17
	v_mfma_f32_32x32x16_bf16 v[48:63], v[92:95], v[0:3], 0
	v_exp_f32_e32 v126, v18
	v_exp_f32_e32 v127, v19
	v_mfma_f32_32x32x16_bf16 v[16:31], v[72:75], v[0:3], 0
	ds_read_b64_tr_b16 v[72:73], v156 offset:24576
	ds_read_b64_tr_b16 v[74:75], v156 offset:26112
	v_mfma_f32_32x32x16_bf16 v[0:15], v[76:79], v[0:3], 0
	ds_read_b64_tr_b16 v[76:77], v156 offset:24640
	ds_read_b64_tr_b16 v[78:79], v156 offset:26176
	v_mfma_f32_32x32x16_bf16 v[0:15], v[84:87], v[88:91], v[0:15]
	v_exp_f32_e32 v128, v96
	v_exp_f32_e32 v129, v97
	v_exp_f32_e32 v130, v98
	v_exp_f32_e32 v131, v99
	v_exp_f32_e32 v132, v100
	v_exp_f32_e32 v133, v101
	v_exp_f32_e32 v134, v102
	v_exp_f32_e32 v135, v103
	v_exp_f32_e32 v120, v120
	v_exp_f32_e32 v123, v123
	v_mfma_f32_32x32x16_bf16 v[48:63], v[92:95], v[88:91], v[48:63]
	v_exp_f32_e32 v121, v121
	v_exp_f32_e32 v122, v122
	v_cvt_pk_bf16_f32 v100, v124, v125
	v_cvt_pk_bf16_f32 v101, v126, v127
	ds_read_b64_tr_b16 v[96:97], v156 offset:27648
	ds_read_b64_tr_b16 v[98:99], v156 offset:29184
	v_cvt_pk_bf16_f32 v86, v120, v121
	v_mfma_f32_32x32x16_bf16 v[16:31], v[80:83], v[88:91], v[16:31]
	ds_read_b64_tr_b16 v[80:81], v156 offset:27712
	ds_read_b64_tr_b16 v[82:83], v156 offset:29248
	v_cvt_pk_bf16_f32 v102, v128, v129
	v_cvt_pk_bf16_f32 v103, v130, v131
	v_cvt_pk_bf16_f32 v84, v132, v133
	v_cvt_pk_bf16_f32 v85, v134, v135
	v_cvt_pk_bf16_f32 v87, v122, v123
	s_waitcnt lgkmcnt(6)
	v_mfma_f32_32x32x16_bf16 v[16:31], v[72:75], v[100:103], v[16:31]
	s_waitcnt lgkmcnt(4)
	v_mfma_f32_32x32x16_bf16 v[0:15], v[76:79], v[100:103], v[0:15]
	v_mfma_f32_32x32x16_bf16 v[48:63], v[92:95], v[100:103], v[48:63]
	s_waitcnt lgkmcnt(2)
	v_mfma_f32_32x32x16_bf16 v[16:31], v[96:99], v[84:87], v[16:31]
	s_waitcnt lgkmcnt(0)
	v_mfma_f32_32x32x16_bf16 v[0:15], v[80:83], v[84:87], v[0:15]
	v_mfma_f32_32x32x16_bf16 v[48:63], v[92:95], v[84:87], v[48:63]
	s_mov_b32 s10, -2
	v_mov_b32_e32 v145, v159
	v_mov_b32_e32 v160, v158
	v_readlane_b32 s82, v254, 54
	s_movk_i32 s83, 0x1000
	v_readlane_b32 s91, v255, 7
	s_waitcnt vmcnt(1)
	ds_write_b128 v153, v[64:67] offset:9216
	s_waitcnt vmcnt(0)
	ds_write_b128 v154, v[68:71] offset:30720
	s_waitcnt lgkmcnt(0)
	s_barrier
	s_branch .LBB0_110
.LBB0_109:
	s_nop 0
	v_exp_f32_e32 v80, v80
	v_exp_f32_e32 v81, v81
	v_exp_f32_e32 v82, v82
	v_exp_f32_e32 v83, v83
	v_exp_f32_e32 v84, v84
	v_exp_f32_e32 v85, v85
	v_exp_f32_e32 v86, v86
	v_exp_f32_e32 v87, v87
	v_exp_f32_e32 v88, v88
	v_exp_f32_e32 v89, v89
	v_exp_f32_e32 v90, v90
	v_exp_f32_e32 v91, v91
	v_exp_f32_e32 v92, v92
	v_exp_f32_e32 v93, v93
	v_exp_f32_e32 v94, v94
	v_exp_f32_e32 v95, v95
	v_cvt_pk_bf16_f32 v80, v80, v81
	v_cvt_pk_bf16_f32 v81, v82, v83
	v_cvt_pk_bf16_f32 v82, v84, v85
	v_cvt_pk_bf16_f32 v83, v86, v87
	v_cvt_pk_bf16_f32 v84, v88, v89
	v_cvt_pk_bf16_f32 v85, v90, v91
	v_cvt_pk_bf16_f32 v86, v92, v93
	v_cvt_pk_bf16_f32 v87, v94, v95
	s_waitcnt lgkmcnt(6)
	v_mfma_f32_32x32x16_bf16 v[16:31], v[132:135], v[80:83], v[16:31]
	v_mov_b64_e32 v[90:91], s[86:87]
	v_mov_b64_e32 v[88:89], s[84:85]
	v_exp_f32_e32 v92, v64
	v_exp_f32_e32 v93, v65
	ds_read_b64_tr_b16 v[64:65], v161 offset:24576
	v_mfma_f32_32x32x16_bf16 v[48:63], v[88:91], v[80:83], v[48:63]
	v_exp_f32_e32 v94, v66
	v_exp_f32_e32 v95, v67
	v_exp_f32_e32 v132, v68
	v_exp_f32_e32 v133, v69
	ds_read_b64_tr_b16 v[66:67], v161 offset:26112
	ds_read_b64_tr_b16 v[68:69], v161 offset:24640
	s_waitcnt lgkmcnt(7)
	v_mfma_f32_32x32x16_bf16 v[0:15], v[128:131], v[80:83], v[0:15]
	v_exp_f32_e32 v134, v70
	v_exp_f32_e32 v135, v71
	v_exp_f32_e32 v128, v72
	v_exp_f32_e32 v129, v73
	ds_read_b64_tr_b16 v[70:71], v161 offset:26176
	ds_read_b64_tr_b16 v[72:73], v161 offset:27648
	v_mfma_f32_32x32x16_bf16 v[48:63], v[88:91], v[84:87], v[48:63]
	v_exp_f32_e32 v130, v74
	v_exp_f32_e32 v131, v75
	v_exp_f32_e32 v162, v76
	v_exp_f32_e32 v163, v77
	ds_read_b64_tr_b16 v[74:75], v161 offset:29184
	ds_read_b64_tr_b16 v[76:77], v161 offset:27712
	s_waitcnt lgkmcnt(9)
	v_mfma_f32_32x32x16_bf16 v[16:31], v[124:127], v[84:87], v[16:31]
	v_exp_f32_e32 v164, v78
	v_exp_f32_e32 v165, v79
	v_cvt_pk_bf16_f32 v80, v92, v93
	v_cvt_pk_bf16_f32 v81, v94, v95
	ds_read_b64_tr_b16 v[78:79], v161 offset:29248
	s_waitcnt lgkmcnt(8)
	v_mfma_f32_32x32x16_bf16 v[0:15], v[120:123], v[84:87], v[0:15]
	v_cvt_pk_bf16_f32 v82, v132, v133
	v_cvt_pk_bf16_f32 v83, v134, v135
	v_cvt_pk_bf16_f32 v84, v128, v129
	v_cvt_pk_bf16_f32 v85, v130, v131
	v_cvt_pk_bf16_f32 v86, v162, v163
	v_cvt_pk_bf16_f32 v87, v164, v165
	s_waitcnt lgkmcnt(6)
	v_mfma_f32_32x32x16_bf16 v[16:31], v[64:67], v[80:83], v[16:31]
	s_and_b32 s17, s11, 1
	s_mul_i32 s19, s17, 0x2400
	s_mulk_i32 s17, 0x3000
	v_add_u32_e32 v182, s19, v153
	s_waitcnt vmcnt(1)
	ds_write_b128 v182, v[96:99]
	v_add_u32_e32 v182, s17, v154
	s_waitcnt vmcnt(0)
	ds_write_b128 v182, v[100:103] offset:18432
	s_waitcnt lgkmcnt(6)
	v_mfma_f32_32x32x16_bf16 v[0:15], v[68:71], v[80:83], v[0:15]
	v_mfma_f32_32x32x16_bf16 v[48:63], v[88:91], v[80:83], v[48:63]
	s_waitcnt lgkmcnt(4)
	v_mfma_f32_32x32x16_bf16 v[16:31], v[72:75], v[84:87], v[16:31]
	s_waitcnt lgkmcnt(2)
	v_mfma_f32_32x32x16_bf16 v[0:15], v[76:79], v[84:87], v[0:15]
	v_mfma_f32_32x32x16_bf16 v[48:63], v[88:91], v[84:87], v[48:63]
	s_add_i32 s10, s10, 1
	s_cmp_eq_u32 s5, s10
	s_waitcnt lgkmcnt(0)
	s_barrier
	s_cbranch_scc1 .LBB0_112
; #define LAS __attribute__((address_space(3)))
; template <int KIND> ...
;     ...
;             if (t + 1 < nt) ATT_LOAD(t + 1);
;             bool active = true;
;             if (KIND == 0 && t < n1) { const int kr = kr_lo + t; active = (kr >= rs_w) && (kr < rs_w + 8); }
;             if (__builtin_amdgcn_readfirstlane((int)active)) {
;                 const int buf = t & 1;
;                 bf16x8 kf[8];
; #pragma unroll
;                 for (int t4 = 0; t4 < 4; ++t4) { kf[2 * t4] = *(const LAS bf16x8*)(lds + buf * KBUF + koff + 32 * t4); kf[2 * t4 + 1] = *(const LAS bf16x8*)(lds + buf * KBUF + koff + 32 * KSTR + 32 * t4); }
;                 __builtin_amdgcn_sched_barrier(0);
;                 f32x16 s0, s1;
; #pragma unroll
;                 for (int t4 = 0; t4 < 4; ++t4) {
;                     s0 = __builtin_amdgcn_mfma_f32_32x32x16_bf16(kf[2 * t4], qf[t4], t4 == 0 ? mneg : s0, 0, 0, 0);
;                     s1 = __builtin_amdgcn_mfma_f32_32x32x16_bf16(kf[2 * t4 + 1], qf[t4], t4 == 0 ? mneg : s1, 0, 0, 0);
;                 }
;                 float ab0[16], ab1[16];
;                 const bool na_lat = (KIND == 0) && (t < n1);
;                 if (na_lat) {
;                     const int bo = boff0 + (kr_lo + t - qr + 7) * 124;
; #pragma unroll
;                     for (int j = 0; j < 16; ++j) {
;                         const int C0 = 8 * (j >> 2) + (j & 3), C1 = 32 + C0;
;                         const float b0 = *(const LAS float*)(lds + bo + 4 * C0), b1 = *(const LAS float*)(lds + bo + 4 * C1);
;                         ab0[j] = ((unsigned)(wb + C0) < 16u) ? b0 : -1e30f;
;                         ab1[j] = ((unsigned)(wb + C1) < 16u) ? b1 : -1e30f;
;                     }
; #pragma unroll
;                     for (int i = 0; i < 8; ++i) { __builtin_amdgcn_sched_group_barrier(0x008, 1, 0); __builtin_amdgcn_sched_group_barrier(0x100, 4, 0); __builtin_amdgcn_sched_group_barrier(0x002, 12, 0); }
;                 }
;                 __builtin_amdgcn_sched_barrier(0);
;                 s16x4 vfa[2][NDT][2], vfb[2][NDT][2];
; #pragma unroll
;                 for (int s = 0; s < 2; ++s)
; #pragma unroll
;                     for (int dt = 0; dt < NDT; ++dt) {
;                         vfa[s][dt][0] = __builtin_amdgcn_ds_read_tr16_b64_v4i16((LAS s16x4*)(lds + buf * VBUF + voff + (16 * s) * VSTR + 64 * dt));
.LBB0_110:
	s_add_i32 s17, s10, -1
	s_add_i32 s11, s10, 4
	s_and_b32 s17, s17, 1
	s_mul_i32 s19, s17, 0x2400
	v_add_u32_e32 v68, s19, v155
	ds_read_b128 v[64:67], v68
	ds_read_b128 v[120:123], v68 offset:32
	ds_read_b128 v[124:127], v68 offset:4608
	ds_read_b128 v[128:131], v68 offset:4640
	ds_read_b128 v[132:135], v68 offset:64
	ds_read_b128 v[162:165], v68 offset:96
	ds_read_b128 v[166:169], v68 offset:4672
	ds_read_b128 v[170:173], v68 offset:4704
	s_cmp_lt_u32 s11, s5
	s_cselect_b32 s20, 0, s5
	s_cselect_b32 s21, s13, s16
	s_lshl_b32 s20, s20, 6
	s_sub_i32 s20, s21, s20
	s_lshl_b32 s21, s11, 6
	s_add_i32 s20, s20, s21
	s_mul_i32 s20, s20, 0xc00
	s_add_u32 s42, s36, s20
	s_addc_u32 s43, s37, 0
	global_load_dwordx4 v[96:99], v184, s[42:43]
	global_load_dwordx4 v[100:103], v184, s[42:43] offset:512
	s_waitcnt lgkmcnt(7)
	v_mfma_f32_32x32x16_bf16 v[80:95], v[64:67], v[116:119], v[32:47]
	s_mulk_i32 s17, 0x3000
	v_add_u32_e32 v161, s17, v156
	s_waitcnt lgkmcnt(5)
	v_mfma_f32_32x32x16_bf16 v[64:79], v[124:127], v[116:119], v[32:47]
	v_mfma_f32_32x32x16_bf16 v[80:95], v[120:123], v[112:115], v[80:95]
	s_waitcnt lgkmcnt(4)
	v_mfma_f32_32x32x16_bf16 v[64:79], v[128:131], v[112:115], v[64:79]
	s_waitcnt lgkmcnt(3)
	v_mfma_f32_32x32x16_bf16 v[80:95], v[132:135], v[108:111], v[80:95]
	ds_read_b64_tr_b16 v[132:133], v161 offset:18432
	ds_read_b64_tr_b16 v[134:135], v161 offset:19968
	ds_read_b64_tr_b16 v[130:131], v161 offset:20032
	ds_read_b64_tr_b16 v[128:129], v161 offset:18496
	ds_read_b64_tr_b16 v[124:125], v161 offset:21504
	ds_read_b64_tr_b16 v[126:127], v161 offset:23040
	ds_read_b64_tr_b16 v[122:123], v161 offset:23104
	ds_read_b64_tr_b16 v[120:121], v161 offset:21568
	s_waitcnt lgkmcnt(9)
	v_mfma_f32_32x32x16_bf16 v[64:79], v[166:169], v[108:111], v[64:79]
	v_mfma_f32_32x32x16_bf16 v[80:95], v[162:165], v[104:107], v[80:95]
	s_waitcnt lgkmcnt(8)
	v_mfma_f32_32x32x16_bf16 v[64:79], v[170:173], v[104:107], v[64:79]
	s_nop 9
	v_max_f32_e32 v162, v95, v95
	s_nop 0
	v_max_f32_e32 v163, v79, v79
	v_max_f32_e32 v162, v163, v162
	v_max3_f32 v163, v162, v80, v64
	v_max3_f32 v162, v162, v81, v65
	s_mov_b32 s17, 0x41000000
	v_max3_f32 v163, v163, v82, v66
	v_max3_f32 v162, v162, v83, v67
	s_nop 0
	v_max3_f32 v163, v163, v84, v68
	v_max3_f32 v162, v162, v85, v69
	s_nop 0
	v_max3_f32 v163, v163, v86, v70
	v_max3_f32 v162, v162, v87, v71
	s_nop 0
	v_max3_f32 v163, v163, v88, v72
	v_max3_f32 v162, v162, v89, v73
	s_nop 0
	v_max3_f32 v163, v163, v90, v74
	v_max3_f32 v162, v162, v91, v75
	s_nop 0
	v_max3_f32 v163, v163, v92, v76
	v_max3_f32 v162, v162, v93, v77
	s_nop 0
	v_max3_f32 v163, v163, v94, v78
	v_max3_f32 v162, v162, v95, v79
	s_nop 0
	v_max_f32_e32 v162, v162, v162
	v_max_f32_e32 v163, v163, v163
	v_max_f32_e32 v162, v163, v162
	v_cmp_lt_f32_e32 vcc, s17, v162
	s_cbranch_vccz .LBB0_109
	ds_bpermute_b32 v163, v157, v162
	s_waitcnt lgkmcnt(0)
	v_max3_f32 v162, v162, v163, 0
	v_exp_f32_e64 v164, -v162
	v_pk_add_f32 v[80:81], v[80:81], v[162:163] op_sel_hi:[1,0] neg_lo:[0,1] neg_hi:[0,1]
	v_pk_add_f32 v[64:65], v[64:65], v[162:163] op_sel_hi:[1,0] neg_lo:[0,1] neg_hi:[0,1]
	v_pk_add_f32 v[82:83], v[82:83], v[162:163] op_sel_hi:[1,0] neg_lo:[0,1] neg_hi:[0,1]
	v_pk_add_f32 v[66:67], v[66:67], v[162:163] op_sel_hi:[1,0] neg_lo:[0,1] neg_hi:[0,1]
	v_pk_add_f32 v[84:85], v[84:85], v[162:163] op_sel_hi:[1,0] neg_lo:[0,1] neg_hi:[0,1]
	v_pk_add_f32 v[68:69], v[68:69], v[162:163] op_sel_hi:[1,0] neg_lo:[0,1] neg_hi:[0,1]
	v_pk_add_f32 v[86:87], v[86:87], v[162:163] op_sel_hi:[1,0] neg_lo:[0,1] neg_hi:[0,1]
	v_pk_add_f32 v[70:71], v[70:71], v[162:163] op_sel_hi:[1,0] neg_lo:[0,1] neg_hi:[0,1]
	v_pk_add_f32 v[88:89], v[88:89], v[162:163] op_sel_hi:[1,0] neg_lo:[0,1] neg_hi:[0,1]
	v_pk_add_f32 v[72:73], v[72:73], v[162:163] op_sel_hi:[1,0] neg_lo:[0,1] neg_hi:[0,1]
	v_pk_add_f32 v[90:91], v[90:91], v[162:163] op_sel_hi:[1,0] neg_lo:[0,1] neg_hi:[0,1]
	v_pk_add_f32 v[74:75], v[74:75], v[162:163] op_sel_hi:[1,0] neg_lo:[0,1] neg_hi:[0,1]
	v_pk_add_f32 v[92:93], v[92:93], v[162:163] op_sel_hi:[1,0] neg_lo:[0,1] neg_hi:[0,1]
	v_pk_add_f32 v[76:77], v[76:77], v[162:163] op_sel_hi:[1,0] neg_lo:[0,1] neg_hi:[0,1]
	v_pk_add_f32 v[94:95], v[94:95], v[162:163] op_sel_hi:[1,0] neg_lo:[0,1] neg_hi:[0,1]
	v_pk_add_f32 v[78:79], v[78:79], v[162:163] op_sel_hi:[1,0] neg_lo:[0,1] neg_hi:[0,1]
	v_pk_mul_f32 v[62:63], v[62:63], v[164:165] op_sel_hi:[1,0]
	v_pk_mul_f32 v[60:61], v[60:61], v[164:165] op_sel_hi:[1,0]
	v_pk_mul_f32 v[58:59], v[58:59], v[164:165] op_sel_hi:[1,0]
	v_pk_mul_f32 v[56:57], v[56:57], v[164:165] op_sel_hi:[1,0]
	v_pk_mul_f32 v[54:55], v[54:55], v[164:165] op_sel_hi:[1,0]
	v_pk_mul_f32 v[52:53], v[52:53], v[164:165] op_sel_hi:[1,0]
	v_pk_mul_f32 v[50:51], v[50:51], v[164:165] op_sel_hi:[1,0]
	v_pk_mul_f32 v[48:49], v[48:49], v[164:165] op_sel_hi:[1,0]
	v_pk_mul_f32 v[14:15], v[14:15], v[164:165] op_sel_hi:[1,0]
	v_pk_mul_f32 v[12:13], v[12:13], v[164:165] op_sel_hi:[1,0]
	v_pk_mul_f32 v[10:11], v[10:11], v[164:165] op_sel_hi:[1,0]
	v_pk_mul_f32 v[8:9], v[8:9], v[164:165] op_sel_hi:[1,0]
	v_pk_mul_f32 v[6:7], v[6:7], v[164:165] op_sel_hi:[1,0]
	v_pk_mul_f32 v[4:5], v[4:5], v[164:165] op_sel_hi:[1,0]
	v_pk_mul_f32 v[2:3], v[2:3], v[164:165] op_sel_hi:[1,0]
	v_pk_mul_f32 v[0:1], v[0:1], v[164:165] op_sel_hi:[1,0]
	v_pk_mul_f32 v[30:31], v[30:31], v[164:165] op_sel_hi:[1,0]
	v_pk_mul_f32 v[28:29], v[28:29], v[164:165] op_sel_hi:[1,0]
	v_pk_mul_f32 v[26:27], v[26:27], v[164:165] op_sel_hi:[1,0]
	v_pk_mul_f32 v[24:25], v[24:25], v[164:165] op_sel_hi:[1,0]
	v_pk_mul_f32 v[22:23], v[22:23], v[164:165] op_sel_hi:[1,0]
	v_pk_mul_f32 v[20:21], v[20:21], v[164:165] op_sel_hi:[1,0]
	v_pk_mul_f32 v[18:19], v[18:19], v[164:165] op_sel_hi:[1,0]
	v_pk_mul_f32 v[16:17], v[16:17], v[164:165] op_sel_hi:[1,0]
	v_sub_f32_e32 v47, v47, v162
	v_sub_f32_e32 v46, v46, v162
	v_sub_f32_e32 v45, v45, v162
	v_sub_f32_e32 v44, v44, v162
	v_sub_f32_e32 v43, v43, v162
	v_sub_f32_e32 v42, v42, v162
	v_sub_f32_e32 v41, v41, v162
	v_sub_f32_e32 v40, v40, v162
	v_sub_f32_e32 v39, v39, v162
	v_sub_f32_e32 v38, v38, v162
	v_sub_f32_e32 v37, v37, v162
	v_sub_f32_e32 v36, v36, v162
	v_sub_f32_e32 v35, v35, v162
	v_sub_f32_e32 v34, v34, v162
	v_sub_f32_e32 v33, v33, v162
	v_sub_f32_e32 v32, v32, v162
	s_branch .LBB0_109

; #define LAS __attribute__((address_space(3)))
; template <int KIND> ...
;     ...
;         { const bf16_t* qp = qkv + (size_t)(qrow0 + qoff + l32) * N + hq * 64 + 8 * hi;
; #pragma unroll
;           for (int t = 0; t < 4; ++t) qf[t] = *(const bf16x8*)(qp + 16 * t); }
;         if (KIND == 0 && !isctx) { LAS float* bt = (LAS float*)(lds + OFF_BIAS); for (int i = tid; i < 465; i += NTHREADS) bt[i] = rpb[h * 465 + i] * LOG2E; }
;         u32x4 kreg[NK], vreg[NVC];
;         const int krow_l = tid >> 3, kpart = tid & 7;
;     ...
;         float m_ref = 0.f; int first = 1;
;         f32x16 o[NDT], lacc, mneg;
; #pragma unroll
;         for (int dt = 0; dt < NDT; ++dt)
; #pragma unroll
;             for (int j = 0; j < 16; ++j) o[dt][j] = 0.f;
; #pragma unroll
;         for (int j = 0; j < 16; ++j) { lacc[j] = 0.f; mneg[j] = 0.f; }
;         const bf16x8 ones = {(short)0x3F80, (short)0x3F80, (short)0x3F80, (short)0x3F80, (short)0x3F80, (short)0x3F80, (short)0x3F80, (short)0x3F80};
;         ATT_LOAD(0); ATT_STORE(0); __syncthreads();
;         const int koff = kidx * KT + l32 * KSTR + 16 * hi;
;         const int voff = OFF_V + (4 * hi + ((lane & 15) >> 2)) * VSTR + (16 * ((lane >> 4) & 1) + 4 * (lane & 3)) * 2;
;     ...
;                 for (int t4 = 0; t4 < 4; ++t4) { kf[2 * t4] = *(const LAS bf16x8*)(lds + buf * KBUF + koff + 32 * t4); kf[2 * t4 + 1] = *(const LAS bf16x8*)(lds + buf * KBUF + koff + 32 * KSTR + 32 * t4); }
;                 __builtin_amdgcn_sched_barrier(0);
;                 f32x16 s0, s1;
; #pragma unroll
;                 for (int t4 = 0; t4 < 4; ++t4) {
;                     s0 = __builtin_amdgcn_mfma_f32_32x32x16_bf16(kf[2 * t4], qf[t4], t4 == 0 ? mneg : s0, 0, 0, 0);
;                     s1 = __builtin_amdgcn_mfma_f32_32x32x16_bf16(kf[2 * t4 + 1], qf[t4], t4 == 0 ? mneg : s1, 0, 0, 0);
;                 }
;                 float ab0[16], ab1[16];
;                 const bool na_lat = (KIND == 0) && (t < n1);
;                 if (na_lat) {
;                     const int bo = boff0 + (kr_lo + t - qr + 7) * 124;
; #pragma unroll
;                     for (int j = 0; j < 16; ++j) {
;                         const int C0 = 8 * (j >> 2) + (j & 3), C1 = 32 + C0;
;                         const float b0 = *(const LAS float*)(lds + bo + 4 * C0), b1 = *(const LAS float*)(lds + bo + 4 * C1);
;                         ab0[j] = ((unsigned)(wb + C0) < 16u) ? b0 : -1e30f;
.LBB0_187:
	s_add_i32 s14, s14, s21
	s_and_b32 s26, s26, 7
	v_add_u32_e32 v2, s14, v199
	v_mov_b64_e32 v[0:1], s[58:59]
	s_movk_i32 s34, 0x1800
	s_lshl_b32 s28, s26, 6
	v_mad_i64_i32 v[2:3], s[4:5], v2, s34, v[0:1]
	s_or_b32 s4, s28, s22
	s_lshl_b32 s96, s26, 7
	s_add_i32 s15, s27, 0x8000
	s_ashr_i32 s5, s4, 31
	v_lshl_add_u64 v[2:3], s[4:5], 1, v[2:3]
	s_and_b64 s[4:5], s[16:17], exec
	v_lshl_add_u64 v[2:3], v[202:203], 1, v[2:3]
	s_cselect_b32 s30, s2, s15
	global_load_dwordx4 v[128:131], v[2:3], off
	global_load_dwordx4 v[132:135], v[2:3], off offset:32
	global_load_dwordx4 v[136:139], v[2:3], off offset:64
	global_load_dwordx4 v[140:143], v[2:3], off offset:96
	s_lshl_b32 s4, s26, 8
	s_add_u32 s4, s58, s4
	s_addc_u32 s5, s59, 0
	s_add_u32 s4, s4, 0x1000
	s_addc_u32 s5, s5, 0
	v_lshl_add_u64 v[210:211], v[204:205], 0, s[96:97]
	v_mov_b64_e32 v[16:17], s[4:5]
	s_add_u32 s36, s58, s96
	s_addc_u32 s37, s59, 0
	s_add_u32 s36, s36, 0x800
	s_addc_u32 s37, s37, 0
	s_mov_b64 s[40:41], s[4:5]
	v_mul_u32_u24_e32 v158, 0x1800, v226
	v_add_u32_e32 v158, v158, v192
	v_mul_u32_u24_e32 v159, 0x1800, v237
	v_add_u32_e32 v159, v159, v206
	s_or_b32 s26, s3, 4
	s_or_b32 s28, s2, 64
	s_add_i32 s27, s27, 0x8040
	s_and_b64 s[16:17], s[16:17], exec
	s_cselect_b32 s27, s28, s27
	v_add_u32_e32 v0, s30, v226
	v_mad_i64_i32 v[0:1], vcc, v0, s34, v[210:211]
	s_mov_b32 m0, s18
	v_add_u32_e32 v2, s30, v237
	global_load_lds_dwordx4 v[0:1], off
	s_add_i32 m0, s18, 0x1c00
	v_mad_i64_i32 v[2:3], vcc, v2, s34, v[16:17]
	global_load_lds_dwordx4 v[0:1], off offset:1024
	v_lshl_add_u64 v[2:3], v[2:3], 0, v[206:207]
	s_add_i32 m0, s18, 0x8000
	v_add_u32_e32 v4, s30, v238
	global_load_lds_dwordx4 v[2:3], off
	v_mad_i64_i32 v[4:5], vcc, v4, s34, v[16:17]
	v_lshl_add_u64 v[4:5], v[4:5], 0, v[208:209]
	s_add_i32 m0, s18, 0xa000
	s_nop 0
	global_load_lds_dwordx4 v[4:5], off
	s_waitcnt vmcnt(0)
	s_barrier
	v_add_u32_e32 v0, s27, v226
	v_mad_i64_i32 v[0:1], vcc, v0, s34, v[210:211]
	s_add_i32 m0, s18, 0x4000
	v_add_u32_e32 v2, s27, v237
	global_load_lds_dwordx4 v[0:1], off
	s_add_i32 m0, s18, 0x5c00
	v_mad_i64_i32 v[2:3], vcc, v2, s34, v[16:17]
	global_load_lds_dwordx4 v[0:1], off offset:1024
	v_lshl_add_u64 v[2:3], v[2:3], 0, v[206:207]
	s_add_i32 m0, s18, 0xc000
	v_add_u32_e32 v4, s27, v238
	global_load_lds_dwordx4 v[2:3], off
	v_mad_i64_i32 v[4:5], vcc, v4, s34, v[16:17]
	v_lshl_add_u64 v[4:5], v[4:5], 0, v[208:209]
	s_add_i32 m0, s18, 0xe000
	s_nop 0
	global_load_lds_dwordx4 v[4:5], off
	v_xor_b32_e32 v144, 32, v235
	v_xor_b32_e32 v145, 64, v235
	v_xor_b32_e32 v146, 0x60, v235
	v_xor_b32_e32 v147, 64, v236
	v_xor_b32_e32 v148, 0x80, v236
	v_xor_b32_e32 v149, 0xc0, v236
	ds_read_b128 v[16:19], v235 offset:4096
	ds_read_b128 v[0:3], v235
	ds_read_b128 v[32:35], v144
	ds_read_b128 v[36:39], v144 offset:4096
	ds_read_b128 v[40:43], v145
	ds_read_b128 v[44:47], v145 offset:4096
	ds_read_b128 v[48:51], v146
	ds_read_b128 v[52:55], v146 offset:4096
	s_waitcnt lgkmcnt(6)
	v_mfma_f32_32x32x16_bf16 v[0:15], v[0:3], v[128:131], 0
	ds_read_b64_tr_b16 v[112:113], v148 offset:32768
	ds_read_b64_tr_b16 v[116:117], v149 offset:32768
	ds_read_b64_tr_b16 v[114:115], v148 offset:34816
	ds_read_b64_tr_b16 v[118:119], v149 offset:34816
	ds_read_b64_tr_b16 v[108:109], v236 offset:36864
	ds_read_b64_tr_b16 v[104:105], v147 offset:36864
	ds_read_b64_tr_b16 v[100:101], v148 offset:36864
	v_mfma_f32_32x32x16_bf16 v[16:31], v[16:19], v[128:131], 0
	ds_read_b64_tr_b16 v[96:97], v149 offset:36864
	ds_read_b64_tr_b16 v[110:111], v236 offset:38912
	ds_read_b64_tr_b16 v[106:107], v147 offset:38912
	ds_read_b64_tr_b16 v[102:103], v148 offset:38912
	ds_read_b64_tr_b16 v[98:99], v149 offset:38912
	s_waitcnt lgkmcnt(14)
	v_mfma_f32_32x32x16_bf16 v[0:15], v[32:35], v[132:135], v[0:15]
	ds_read_b64_tr_b16 v[32:33], v236 offset:32768
	ds_read_b64_tr_b16 v[34:35], v236 offset:34816
	v_mfma_f32_32x32x16_bf16 v[16:31], v[36:39], v[132:135], v[16:31]
	ds_read_b64_tr_b16 v[36:37], v147 offset:32768
	ds_read_b64_tr_b16 v[38:39], v147 offset:34816
	v_mfma_f32_32x32x16_bf16 v[0:15], v[40:43], v[136:139], v[0:15]
	v_mfma_f32_32x32x16_bf16 v[16:31], v[44:47], v[136:139], v[16:31]
	s_waitcnt lgkmcnt(14)
	v_mfma_f32_32x32x16_bf16 v[0:15], v[48:51], v[140:143], v[0:15]
	v_mfma_f32_32x32x16_bf16 v[16:31], v[52:55], v[140:143], v[16:31]
	s_nop 10
	v_max_f32_e32 v40, v15, v15
	v_max_f32_e32 v41, v31, v31
	v_max_f32_e32 v40, v41, v40
	v_max3_f32 v41, v40, v0, v16
	v_max3_f32 v40, v40, v1, v17
	s_nop 0
	v_max3_f32 v41, v41, v2, v18
	v_max3_f32 v40, v40, v3, v19
	s_nop 0
	v_max3_f32 v41, v41, v4, v20
	v_max3_f32 v40, v40, v5, v21
	s_nop 0
	v_max3_f32 v41, v41, v6, v22
	v_max3_f32 v40, v40, v7, v23
	s_nop 0
	v_max3_f32 v41, v41, v8, v24
	v_max3_f32 v40, v40, v9, v25
	s_nop 0
	v_max3_f32 v41, v41, v10, v26
	v_max3_f32 v40, v40, v11, v27
	s_nop 0
	v_max3_f32 v41, v41, v12, v28
	v_max3_f32 v40, v40, v13, v29
	s_nop 0
	v_max3_f32 v41, v41, v14, v30
	v_max3_f32 v40, v40, v15, v31
	s_nop 0
	v_max_f32_e32 v40, v40, v40
	v_max_f32_e32 v41, v41, v41
	v_max_f32_e32 v40, v41, v40
	ds_bpermute_b32 v41, v197, v40
	s_waitcnt lgkmcnt(0)
; #define LAS __attribute__((address_space(3)))
; template <int KIND> ...
;     ...
;                     const float alpha = first ? 1.0f : __builtin_amdgcn_exp2f(-d);
;                     m_ref += d;
; #pragma unroll
;                     for (int j = 0; j < 16; ++j) { mneg[j] -= d; s0[j] -= d; s1[j] -= d; lacc[j] *= alpha; }
; #pragma unroll
;                     for (int dt = 0; dt < NDT; ++dt)
; #pragma unroll
;                         for (int j = 0; j < 16; ++j) o[dt][j] *= alpha;
;                     first = 0;
;                 }
; #pragma unroll
;                 for (int j = 0; j < 16; ++j) s0[j] = __builtin_amdgcn_exp2f(s0[j]);
;                 bf16x8 pf[4];
; #pragma unroll
;                 for (int s = 0; s < 2; ++s) { u32x4 w; w.x = pk2n(s0[8 * s + 0], s0[8 * s + 1]); w.y = pk2n(s0[8 * s + 2], s0[8 * s + 3]); w.z = pk2n(s0[8 * s + 4], s0[8 * s + 5]); w.w = pk2n(s0[8 * s + 6], s0[8 * s + 7]);
;                     pf[s] = __builtin_bit_cast(bf16x8, w); }
;                 __builtin_amdgcn_sched_barrier(0);
; #pragma unroll
;                 for (int s = 0; s < 2; ++s)
; #pragma unroll
;                     for (int dt = 0; dt < NDT; ++dt) {
;                         vfb[s][dt][0] = __builtin_amdgcn_ds_read_tr16_b64_v4i16((LAS s16x4*)(lds + buf * VBUF + voff + (16 * (s + 2)) * VSTR + 64 * dt));
;                         vfb[s][dt][1] = __builtin_amdgcn_ds_read_tr16_b64_v4i16((LAS s16x4*)(lds + buf * VBUF + voff + (16 * (s + 2) + 8) * VSTR + 64 * dt)); }
;                 {
;                     constexpr int NM = 2 * (1 + NDT);
;                     int mi = 0;
; #pragma unroll
;                     for (int s = 0; s < 2; ++s) {
;                         lacc = __builtin_amdgcn_mfma_f32_32x32x16_bf16(ones, pf[s], lacc, 0, 0, 0);
; #pragma unroll
;                         for (int j = (mi * 16) / NM; j < ((mi + 1) * 16) / NM; ++j) s1[j] = __builtin_amdgcn_exp2f(s1[j]);
;                         ++mi;
; #pragma unroll
;                         for (int dt = 0; dt < NDT; ++dt) {
;                             const s16x4 va = vfa[s][dt][0], vb = vfa[s][dt][1];
;                             const bf16x8 vf = {va[0], va[1], va[2], va[3], vb[0], vb[1], vb[2], vb[3]};
;                             o[dt] = __builtin_amdgcn_mfma_f32_32x32x16_bf16(vf, pf[s], o[dt], 0, 0, 0);
; #pragma unroll
	v_max_f32_e32 v41, v41, v41
	v_max_f32_e32 v40, v40, v41
	v_sub_f32_e32 v0, v0, v40
	v_sub_f32_e32 v1, v1, v40
	v_sub_f32_e32 v2, v2, v40
	v_sub_f32_e32 v3, v3, v40
	v_sub_f32_e32 v4, v4, v40
	v_sub_f32_e32 v5, v5, v40
	v_sub_f32_e32 v6, v6, v40
	v_sub_f32_e32 v7, v7, v40
	v_sub_f32_e32 v8, v8, v40
	v_sub_f32_e32 v9, v9, v40
	v_sub_f32_e32 v10, v10, v40
	v_sub_f32_e32 v11, v11, v40
	v_sub_f32_e32 v12, v12, v40
	v_sub_f32_e32 v13, v13, v40
	v_sub_f32_e32 v14, v14, v40
	v_sub_f32_e32 v15, v15, v40
	v_exp_f32_e32 v0, v0
	v_exp_f32_e32 v1, v1
	v_exp_f32_e32 v2, v2
	v_exp_f32_e32 v3, v3
	v_exp_f32_e32 v4, v4
	v_exp_f32_e32 v5, v5
	v_exp_f32_e32 v6, v6
	v_exp_f32_e32 v7, v7
	v_exp_f32_e32 v8, v8
	v_exp_f32_e32 v9, v9
	v_exp_f32_e32 v10, v10
	v_exp_f32_e32 v11, v11
	v_exp_f32_e32 v12, v12
	v_exp_f32_e32 v13, v13
	v_exp_f32_e32 v14, v14
	v_exp_f32_e32 v15, v15
	v_sub_f32_e32 v64, 0, v40
	v_sub_f32_e32 v16, v16, v40
	v_sub_f32_e32 v17, v17, v40
	v_sub_f32_e32 v18, v18, v40
	v_sub_f32_e32 v19, v19, v40
	v_sub_f32_e32 v20, v20, v40
	v_sub_f32_e32 v21, v21, v40
	v_sub_f32_e32 v22, v22, v40
	v_sub_f32_e32 v23, v23, v40
	v_sub_f32_e32 v24, v24, v40
	v_mov_b32_e32 v65, v64
	v_mov_b32_e32 v66, v64
	v_mov_b32_e32 v67, v64
	v_mov_b32_e32 v68, v64
	v_mov_b32_e32 v69, v64
	v_mov_b32_e32 v70, v64
	v_mov_b32_e32 v71, v64
	v_mov_b32_e32 v72, v64
	v_mov_b32_e32 v73, v64
	v_mov_b32_e32 v74, v64
	v_mov_b32_e32 v75, v64
	v_mov_b32_e32 v76, v64
	v_mov_b32_e32 v77, v64
	v_mov_b32_e32 v78, v64
	v_mov_b32_e32 v79, v64
	v_cvt_pk_bf16_f32 v0, v0, v1
	v_cvt_pk_bf16_f32 v1, v2, v3
	v_cvt_pk_bf16_f32 v2, v4, v5
	v_cvt_pk_bf16_f32 v3, v6, v7
	v_sub_f32_e32 v160, v25, v40
	v_sub_f32_e32 v161, v26, v40
	v_sub_f32_e32 v162, v27, v40
	v_sub_f32_e32 v163, v28, v40
	v_sub_f32_e32 v164, v29, v40
	v_sub_f32_e32 v165, v30, v40
	v_sub_f32_e32 v166, v31, v40
	v_cvt_pk_bf16_f32 v120, v8, v9
	v_cvt_pk_bf16_f32 v121, v10, v11
	v_cvt_pk_bf16_f32 v122, v12, v13
	v_cvt_pk_bf16_f32 v123, v14, v15
	v_mfma_f32_32x32x16_bf16 v[48:63], v[32:35], v[0:3], 0
	v_mov_b64_e32 v[126:127], s[86:87]
	v_mov_b64_e32 v[124:125], s[84:85]
	v_exp_f32_e32 v167, v16
	s_nop 0
	v_mfma_f32_32x32x16_bf16 v[80:95], v[124:127], v[0:3], 0
	v_exp_f32_e32 v168, v17
	v_exp_f32_e32 v169, v18
	v_exp_f32_e32 v170, v19
	v_mfma_f32_32x32x16_bf16 v[32:47], v[36:39], v[0:3], 0
	v_exp_f32_e32 v171, v20
	v_exp_f32_e32 v172, v21
	v_exp_f32_e32 v173, v22
	v_mfma_f32_32x32x16_bf16 v[80:95], v[124:127], v[120:123], v[80:95]
	v_exp_f32_e32 v174, v23
	v_exp_f32_e32 v175, v24
	v_exp_f32_e32 v176, v160
	v_mfma_f32_32x32x16_bf16 v[16:31], v[112:115], v[0:3], 0
	v_exp_f32_e32 v177, v161
	v_exp_f32_e32 v178, v162
	v_exp_f32_e32 v179, v163
	ds_read_b64_tr_b16 v[112:113], v236 offset:40960
	ds_read_b64_tr_b16 v[114:115], v236 offset:43008
	ds_read_b64_tr_b16 v[160:161], v148 offset:40960
	ds_read_b64_tr_b16 v[162:163], v148 offset:43008
	v_mfma_f32_32x32x16_bf16 v[0:15], v[116:119], v[0:3], 0
	v_exp_f32_e32 v180, v164
	v_exp_f32_e32 v181, v166
	v_exp_f32_e32 v182, v165
	v_mfma_f32_32x32x16_bf16 v[48:63], v[108:111], v[120:123], v[48:63]
	v_cvt_pk_bf16_f32 v116, v167, v168
	v_cvt_pk_bf16_f32 v117, v169, v170
	v_cvt_pk_bf16_f32 v118, v171, v172
	ds_read_b64_tr_b16 v[108:109], v147 offset:40960
	ds_read_b64_tr_b16 v[110:111], v147 offset:43008
	ds_read_b64_tr_b16 v[168:169], v236 offset:45056
	ds_read_b64_tr_b16 v[170:171], v236 offset:47104
	v_mfma_f32_32x32x16_bf16 v[32:47], v[104:107], v[120:123], v[32:47]
	v_cvt_pk_bf16_f32 v119, v173, v174
	v_cvt_pk_bf16_f32 v164, v175, v176
	v_cvt_pk_bf16_f32 v165, v177, v178
	ds_read_b64_tr_b16 v[104:105], v149 offset:40960
	ds_read_b64_tr_b16 v[106:107], v149 offset:43008
	ds_read_b64_tr_b16 v[172:173], v148 offset:45056
	ds_read_b64_tr_b16 v[174:175], v148 offset:47104
	v_mfma_f32_32x32x16_bf16 v[16:31], v[100:103], v[120:123], v[16:31]
	v_cvt_pk_bf16_f32 v166, v179, v180
	v_cvt_pk_bf16_f32 v167, v182, v181
	ds_read_b64_tr_b16 v[100:101], v147 offset:45056
	ds_read_b64_tr_b16 v[102:103], v147 offset:47104
	ds_read_b64_tr_b16 v[176:177], v149 offset:45056
	ds_read_b64_tr_b16 v[178:179], v149 offset:47104
	v_mfma_f32_32x32x16_bf16 v[0:15], v[96:99], v[120:123], v[0:15]
	v_mfma_f32_32x32x16_bf16 v[80:95], v[124:127], v[116:119], v[80:95]
	s_waitcnt lgkmcnt(14)
	v_mfma_f32_32x32x16_bf16 v[48:63], v[112:115], v[116:119], v[48:63]
	s_waitcnt lgkmcnt(10)
	v_mfma_f32_32x32x16_bf16 v[32:47], v[108:111], v[116:119], v[32:47]
	v_mfma_f32_32x32x16_bf16 v[16:31], v[160:163], v[116:119], v[16:31]
	s_waitcnt lgkmcnt(6)
	v_mfma_f32_32x32x16_bf16 v[0:15], v[104:107], v[116:119], v[0:15]
	v_mfma_f32_32x32x16_bf16 v[80:95], v[124:127], v[164:167], v[80:95]
	v_mfma_f32_32x32x16_bf16 v[48:63], v[168:171], v[164:167], v[48:63]
	s_waitcnt lgkmcnt(2)
	v_mfma_f32_32x32x16_bf16 v[32:47], v[100:103], v[164:167], v[32:47]
	v_mfma_f32_32x32x16_bf16 v[16:31], v[172:175], v[164:167], v[16:31]
	s_waitcnt lgkmcnt(0)
	v_mfma_f32_32x32x16_bf16 v[0:15], v[176:179], v[164:167], v[0:15]
	v_lshl_add_u64 v[212:213], s[4:5], 0, v[206:207]
	v_lshl_add_u64 v[214:215], s[4:5], 0, v[208:209]
	s_mov_b32 s16, -3
	v_mov_b32_e32 v248, v245
	v_mov_b32_e32 v249, v244
	v_mov_b32_e32 v250, v243
	s_waitcnt vmcnt(0)
	s_waitcnt lgkmcnt(0)
	s_barrier
	s_branch .LBB0_189
.LBB0_188:
	s_add_i32 s16, s16, 1
	s_cmp_eq_u32 s3, s16
	s_waitcnt vmcnt(0) lgkmcnt(0)
	s_barrier
	s_cbranch_scc1 .LBB0_195
.LBB0_189:
	s_add_i32 s17, s16, 5
	s_cmp_lt_u32 s17, s26
	s_cselect_b64 s[4:5], -1, 0
	s_cmp_ge_u32 s17, s26
	s_cbranch_scc1 .LBB0_191
	s_cmp_lt_u32 s17, s3
	s_cselect_b32 s27, 0, s3
	s_cselect_b32 s28, s2, s15
	s_lshl_b32 s27, s27, 6
	s_sub_i32 s27, s28, s27
	s_lshl_b32 s28, s17, 6
	s_add_i32 s27, s27, s28
	s_mul_i32 s27, s27, 0x1800
	s_and_b32 s29, s17, 1
	s_lshl_b32 s29, s29, 14
	s_add_i32 s29, s29, s18
	s_add_u32 s42, s36, s27
	s_addc_u32 s43, s37, 0
	s_add_u32 s44, s40, s27
	s_addc_u32 s45, s41, 0
	s_add_u32 s60, s44, 0x30000
	s_addc_u32 s61, s45, 0
	s_mov_b32 m0, s29
	s_nop 0
	global_load_lds_dwordx4 v158, s[42:43]
	s_add_i32 m0, s29, 0x1c00
	s_nop 0
	global_load_lds_dwordx4 v158, s[42:43] offset:1024
	s_add_i32 m0, s29, 0x8000
	s_nop 0
	global_load_lds_dwordx4 v159, s[44:45]
	s_add_i32 m0, s29, 0xa000
	s_nop 0
	global_load_lds_dwordx4 v159, s[60:61]
